# attention loop heads: one vmcnt wait instead of a per-store ladder (loads landed an iteration earlier)
# speedup vs baseline: 1.1490x; 1.0036x over previous
.LBB0_1939:
	s_barrier
	s_cmp_ge_u32 s14, s13
	s_waitcnt vmcnt(0)
	ds_write_b128 v215, v[28:31]
	ds_write_b128 v216, v[24:27]
	ds_write_b128 v217, v[32:35]
	ds_write_b128 v218, v[36:39] offset:13312
	ds_write_b128 v218, v[44:47] offset:17920
	s_nop 0
	ds_write_b128 v215, v[52:55] offset:22528
	ds_write_b128 v216, v[56:59] offset:22528
	ds_write_b128 v217, v[60:63] offset:22528
	s_cselect_b64 s[6:7], -1, 0
	s_and_b64 vcc, exec, s[6:7]
	ds_write_b128 v218, v[64:67] offset:35840
	ds_write_b128 v218, v[68:71] offset:40448
	s_waitcnt lgkmcnt(0)
	s_barrier
	s_cbranch_vccnz .LBB0_1941
	s_sub_i32 s8, s2, 64
	s_mov_b32 s9, s77
	s_lshl_b64 s[8:9], s[8:9], 1
	s_add_u32 s8, s4, s8
	s_addc_u32 s9, s5, s9
	s_add_u32 s20, s0, 0xffffd000
	s_addc_u32 s21, s1, -1
	global_load_dwordx4 v[24:27], v236, s[20:21]
	global_load_dwordx4 v[28:31], v219, s[20:21]
	global_load_dwordx4 v[32:35], v241, s[20:21]
	global_load_dwordx4 v[36:39], v237, s[8:9]
	global_load_dwordx4 v[44:47], v238, s[8:9]
	s_mov_b32 s3, s77
	s_lshl_b64 s[8:9], s[2:3], 1
	s_add_u32 s8, s4, s8
	s_addc_u32 s9, s5, s9
	global_load_dwordx4 v[52:55], v219, s[0:1]
	global_load_dwordx4 v[56:59], v236, s[0:1]
	global_load_dwordx4 v[60:63], v241, s[0:1]
	global_load_dwordx4 v[64:67], v237, s[8:9]
	global_load_dwordx4 v[68:71], v238, s[8:9]

.LBB0_1994:
	s_waitcnt lgkmcnt(0)
	s_barrier
	s_mov_b32 s12, -1
	s_waitcnt vmcnt(0)
	ds_write_b128 v214, v[84:87]
	ds_write_b128 v214, v[88:91] offset:4608
	s_cmp_ge_i32 s2, s70
	s_mov_b32 s3, s2
	ds_write_b128 v218, v[92:95] offset:13312
	ds_write_b128 v218, v[96:99] offset:17920
	s_waitcnt lgkmcnt(0)
	s_barrier
	s_cbranch_scc0 .LBB0_2001
